# x residual tile preloaded into the accumulators during the P3/P4 grid barrier (acc = x/gate, out = gate*acc), epilogue x loads removed
# speedup vs baseline: 1.0274x; 1.0072x over previous
.LBB0_509:
	s_cmp_gt_i32 s27, 4
	s_cselect_b64 s[4:5], -1, 0
	s_and_b64 s[6:7], s[30:31], s[4:5]
	s_andn2_b64 vcc, exec, s[6:7]
	s_cbranch_vccnz .LBB0_559
	s_waitcnt vmcnt(0)
	v_cmp_eq_u32_e32 vcc, 0, v0
	s_waitcnt vmcnt(0) lgkmcnt(0)
	s_barrier
	s_cmp_eq_u32 s28, 0
	s_cbranch_scc1 .Lxpre_skip_a
	s_load_dwordx2 s[90:91], s[0:1], 0x0
	s_and_b32 s80, s2, 7
	s_lshl_b32 s80, s80, 2
	s_bfe_u32 s81, s2, 0x20003
	s_add_i32 s80, s80, s81
	s_lshr_b32 s81, s2, 5
	s_lshl_b32 s80, s80, 21
	s_lshl_b32 s81, s81, 10
	s_add_u32 s80, s80, s81
	s_lshr_b32 s82, s28, 2
	s_lshl_b32 s82, s82, 19
	s_add_u32 s80, s80, s82
	s_and_b32 s82, s28, 3
	s_lshl_b32 s82, s82, 7
	s_add_u32 s80, s80, s82
	v_and_b32_e32 v202, 15, v0
	v_lshlrev_b32_e32 v202, 13, v202
	v_bfe_u32 v203, v0, 4, 2
	v_lshl_or_b32 v202, v203, 5, v202
	s_waitcnt lgkmcnt(0)
	s_add_u32 s90, s90, s80
	s_addc_u32 s91, s91, 0
	global_load_dwordx4 v[126:129], v202, s[90:91] nt
	global_load_dwordx4 v[122:125], v202, s[90:91] offset:16 nt
	global_load_dwordx4 v[118:121], v202, s[90:91] offset:512 nt
	global_load_dwordx4 v[114:117], v202, s[90:91] offset:528 nt
	s_add_u32 s90, s90, 0x20000
	s_addc_u32 s91, s91, 0
	global_load_dwordx4 v[110:113], v202, s[90:91] nt
	global_load_dwordx4 v[106:109], v202, s[90:91] offset:16 nt
	global_load_dwordx4 v[102:105], v202, s[90:91] offset:512 nt
	global_load_dwordx4 v[98:101], v202, s[90:91] offset:528 nt
	s_add_u32 s90, s90, 0x20000
	s_addc_u32 s91, s91, 0
	global_load_dwordx4 v[94:97], v202, s[90:91] nt
	global_load_dwordx4 v[90:93], v202, s[90:91] offset:16 nt
	global_load_dwordx4 v[86:89], v202, s[90:91] offset:512 nt
	global_load_dwordx4 v[154:157], v202, s[90:91] offset:528 nt
	s_add_u32 s90, s90, 0x20000
	s_addc_u32 s91, s91, 0
	global_load_dwordx4 v[82:85], v202, s[90:91] nt
	global_load_dwordx4 v[158:161], v202, s[90:91] offset:16 nt
	global_load_dwordx4 v[162:165], v202, s[90:91] offset:512 nt
	global_load_dwordx4 v[166:169], v202, s[90:91] offset:528 nt
	s_add_u32 s90, s90, 0xa0000
	s_addc_u32 s91, s91, 0
	global_load_dwordx4 v[170:173], v202, s[90:91] nt
	global_load_dwordx4 v[174:177], v202, s[90:91] offset:16 nt
	global_load_dwordx4 v[178:181], v202, s[90:91] offset:512 nt
	global_load_dwordx4 v[182:185], v202, s[90:91] offset:528 nt
	s_add_u32 s90, s90, 0x20000
	s_addc_u32 s91, s91, 0
	global_load_dwordx4 v[186:189], v202, s[90:91] nt
	global_load_dwordx4 v[190:193], v202, s[90:91] offset:16 nt
	global_load_dwordx4 v[194:197], v202, s[90:91] offset:512 nt
	global_load_dwordx4 v[198:201], v202, s[90:91] offset:528 nt
	s_add_u32 s90, s90, 0x20000
	s_addc_u32 s91, s91, 0
	global_load_dwordx4 v[206:209], v202, s[90:91] nt
	global_load_dwordx4 v[210:213], v202, s[90:91] offset:16 nt
	global_load_dwordx4 v[214:217], v202, s[90:91] offset:512 nt
	global_load_dwordx4 v[218:221], v202, s[90:91] offset:528 nt
	s_add_u32 s90, s90, 0x20000
	s_addc_u32 s91, s91, 0
	global_load_dwordx4 v[222:225], v202, s[90:91] nt
	global_load_dwordx4 v[226:229], v202, s[90:91] offset:16 nt
	global_load_dwordx4 v[230:233], v202, s[90:91] offset:512 nt
	global_load_dwordx4 v[234:237], v202, s[90:91] offset:528 nt
.Lxpre_skip_a:
	s_and_saveexec_b64 s[6:7], vcc
	s_cbranch_execz .LBB0_558
	v_mov_b32_e32 v1, s72
	s_waitcnt vmcnt(0) expcnt(0) lgkmcnt(0)
	ds_read_b32 v3, v1
	ds_read_b32 v1, v1 offset:4
	s_waitcnt lgkmcnt(1)
	v_cmp_ne_u32_e32 vcc, 0, v3
	s_cbranch_vccnz .LBB0_526
	v_readlane_b32 s8, v255, 0
	v_readlane_b32 s9, v255, 1
	s_load_dwordx2 s[12:13], s[8:9], 0x4
	s_add_u32 s8, s24, 0x1000
	s_addc_u32 s9, s25, 0
	s_add_u32 s10, s24, 0x1100
	s_addc_u32 s11, s25, 0
	s_waitcnt lgkmcnt(0)
	s_mul_i32 s22, s12, s3
	s_add_u32 s12, s24, 0x1200
	s_mul_i32 s22, s22, s13
	s_addc_u32 s13, s25, 0
	s_add_u32 s14, s24, 0x1300
	s_addc_u32 s15, s25, 0
	s_mov_b32 s23, 1
	v_mov_b32_e32 v17, 0
	s_branch .LBB0_514

.LBB0_559:
	s_cmp_lg_u32 s28, 0
	s_cbranch_scc1 .Lxpre_skip_b
	s_load_dwordx2 s[90:91], s[0:1], 0x0
	s_and_b32 s80, s2, 7
	s_lshl_b32 s80, s80, 2
	s_bfe_u32 s81, s2, 0x20003
	s_add_i32 s80, s80, s81
	s_lshr_b32 s81, s2, 5
	s_lshl_b32 s80, s80, 21
	s_lshl_b32 s81, s81, 10
	s_add_u32 s80, s80, s81
	s_lshr_b32 s82, s28, 2
	s_lshl_b32 s82, s82, 19
	s_add_u32 s80, s80, s82
	s_and_b32 s82, s28, 3
	s_lshl_b32 s82, s82, 7
	s_add_u32 s80, s80, s82
	v_and_b32_e32 v202, 15, v0
	v_lshlrev_b32_e32 v202, 13, v202
	v_bfe_u32 v203, v0, 4, 2
	v_lshl_or_b32 v202, v203, 5, v202
	s_waitcnt lgkmcnt(0)
	s_add_u32 s90, s90, s80
	s_addc_u32 s91, s91, 0
	global_load_dwordx4 v[126:129], v202, s[90:91] nt
	global_load_dwordx4 v[122:125], v202, s[90:91] offset:16 nt
	global_load_dwordx4 v[118:121], v202, s[90:91] offset:512 nt
	global_load_dwordx4 v[114:117], v202, s[90:91] offset:528 nt
	s_add_u32 s90, s90, 0x20000
	s_addc_u32 s91, s91, 0
	global_load_dwordx4 v[110:113], v202, s[90:91] nt
	global_load_dwordx4 v[106:109], v202, s[90:91] offset:16 nt
	global_load_dwordx4 v[102:105], v202, s[90:91] offset:512 nt
	global_load_dwordx4 v[98:101], v202, s[90:91] offset:528 nt
	s_add_u32 s90, s90, 0x20000
	s_addc_u32 s91, s91, 0
	global_load_dwordx4 v[94:97], v202, s[90:91] nt
	global_load_dwordx4 v[90:93], v202, s[90:91] offset:16 nt
	global_load_dwordx4 v[86:89], v202, s[90:91] offset:512 nt
	global_load_dwordx4 v[154:157], v202, s[90:91] offset:528 nt
	s_add_u32 s90, s90, 0x20000
	s_addc_u32 s91, s91, 0
	global_load_dwordx4 v[82:85], v202, s[90:91] nt
	global_load_dwordx4 v[158:161], v202, s[90:91] offset:16 nt
	global_load_dwordx4 v[162:165], v202, s[90:91] offset:512 nt
	global_load_dwordx4 v[166:169], v202, s[90:91] offset:528 nt
	s_add_u32 s90, s90, 0xa0000
	s_addc_u32 s91, s91, 0
	global_load_dwordx4 v[170:173], v202, s[90:91] nt
	global_load_dwordx4 v[174:177], v202, s[90:91] offset:16 nt
	global_load_dwordx4 v[178:181], v202, s[90:91] offset:512 nt
	global_load_dwordx4 v[182:185], v202, s[90:91] offset:528 nt
	s_add_u32 s90, s90, 0x20000
	s_addc_u32 s91, s91, 0
	global_load_dwordx4 v[186:189], v202, s[90:91] nt
	global_load_dwordx4 v[190:193], v202, s[90:91] offset:16 nt
	global_load_dwordx4 v[194:197], v202, s[90:91] offset:512 nt
	global_load_dwordx4 v[198:201], v202, s[90:91] offset:528 nt
	s_add_u32 s90, s90, 0x20000
	s_addc_u32 s91, s91, 0
	global_load_dwordx4 v[206:209], v202, s[90:91] nt
	global_load_dwordx4 v[210:213], v202, s[90:91] offset:16 nt
	global_load_dwordx4 v[214:217], v202, s[90:91] offset:512 nt
	global_load_dwordx4 v[218:221], v202, s[90:91] offset:528 nt
	s_add_u32 s90, s90, 0x20000
	s_addc_u32 s91, s91, 0
	global_load_dwordx4 v[222:225], v202, s[90:91] nt
	global_load_dwordx4 v[226:229], v202, s[90:91] offset:16 nt
	global_load_dwordx4 v[230:233], v202, s[90:91] offset:512 nt
	global_load_dwordx4 v[234:237], v202, s[90:91] offset:528 nt

.LBB0_616:
	s_cmp_lt_i32 s26, 6
	s_cselect_b64 s[6:7], -1, 0
	s_and_b64 s[4:5], s[6:7], s[4:5]
	s_andn2_b64 vcc, exec, s[4:5]
	s_cbranch_vccnz .LBB0_664
	s_cmpk_gt_i32 s2, 0xff
	v_readfirstlane_b32 s33, v0
	s_cbranch_scc1 .LBB0_664
	s_and_b32 s80, s2, 7
	s_lshl_b32 s80, s80, 2
	s_bfe_u32 s81, s2, 0x20003
	s_add_i32 s80, s80, s81
	s_lshr_b32 s80, s80, 4
	s_mul_i32 s80, s80, 0x6000
	s_lshr_b32 s81, s2, 5
	s_lshl_b32 s81, s81, 10
	s_add_u32 s80, s80, s81
	s_lshr_b32 s81, s33, 6
	s_and_b32 s81, s81, 3
	s_lshl_b32 s81, s81, 7
	s_add_u32 s80, s80, s81
	s_add_u32 s80, s80, 0x2904000
	s_add_u32 s92, s24, s80
	s_addc_u32 s93, s25, 0
	v_bfe_u32 v205, v0, 4, 2
	v_lshlrev_b32_e32 v205, 5, v205
	global_load_dwordx4 v[146:149], v205, s[92:93]
	global_load_dwordx4 v[242:245], v205, s[92:93] offset:16
	global_load_dwordx4 v[246:249], v205, s[92:93] offset:512
	global_load_dwordx4 v[250:253], v205, s[92:93] offset:528
	v_lshrrev_b32_e32 v150, 1, v0
	s_waitcnt lgkmcnt(0)
	v_lshrrev_b32_e32 v4, 5, v0
	v_lshlrev_b32_e32 v1, 4, v0
	v_and_b32_e32 v2, 32, v0
	v_and_b32_e32 v3, 24, v150
	v_and_b32_e32 v4, 4, v4
	v_bfe_u32 v5, v0, 2, 2
	s_add_u32 s37, s24, 0xe000000
	v_bfe_u32 v12, v0, 2, 4
	v_bitop3_b32 v10, v1, v2, 48 bitop3:0x6c
	v_and_b32_e32 v11, 64, v0
	v_or3_b32 v3, v4, v5, v3
	v_lshrrev_b32_e32 v4, 3, v0
	v_or_b32_e32 v13, 0x2000, v1
	s_addc_u32 s38, s25, 0
	v_or_b32_e32 v2, v10, v11
	v_and_or_b32 v5, v4, 48, v12
	v_and_or_b32 v4, v4, 32, v3
	v_lshrrev_b32_e32 v1, 7, v13
	s_movk_i32 s4, 0x70
	s_add_u32 s39, s24, 0x1e00000
	v_lshl_or_b32 v132, v4, 12, v2
	v_and_or_b32 v4, v1, s4, v12
	s_movk_i32 s4, 0x60
	s_addc_u32 s40, s25, 0
	s_ashr_i32 s42, s2, 31
	v_and_or_b32 v1, v1, s4, v3
	s_lshr_b32 s4, s42, 29
	s_add_i32 s4, s2, s4
	s_ashr_i32 s5, s4, 3
	s_and_b32 s4, s4, -8
	s_lshr_b32 s11, s33, 6
	s_sub_i32 s4, s2, s4
	s_lshr_b32 s36, s33, 8
	s_lshl_b32 s41, s11, 10
	s_lshl_b32 s7, s4, 5
	s_mul_i32 s6, s4, 33
	s_cmp_lt_i32 s4, 0
	s_cselect_b32 s4, s6, s7
	s_add_i32 s4, s4, s5
	s_ashr_i32 s5, s4, 31
	s_lshr_b32 s5, s5, 27
	s_add_i32 s5, s4, s5
	s_ashr_i32 s6, s5, 5
	s_and_b32 s5, s5, 0xffe0
	s_sub_i32 s5, s4, s5
	s_bfe_i32 s4, s5, 0x80000
	s_bfe_u32 s4, s4, 0x2000d
	s_add_i32 s7, s5, s4
	s_bfe_i32 s4, s7, 0x80000
	s_and_b32 s7, s7, 0xfc
	s_sub_i32 s5, s5, s7
	s_lshl_b32 s6, s6, 2
	s_sext_i32_i16 s4, s4
	s_sext_i32_i8 s5, s5
	s_lshr_b32 s4, s4, 2
	s_add_i32 s8, s6, s5
	s_ashr_i32 s9, s8, 31
	s_bfe_i64 s[12:13], s[4:5], 0x100000
	s_lshl_b64 s[6:7], s[8:9], 20
	s_lshl_b64 s[12:13], s[12:13], 20
	s_add_u32 s28, s39, s12
	s_addc_u32 s29, s40, s13
	s_add_i32 s43, s41, 0
	s_add_i32 m0, s43, 0x10000
	v_lshl_or_b32 v136, v1, 12, v2
	global_load_lds_dwordx4 v132, s[28:29]
	s_add_i32 m0, s43, 0x12000
	s_add_u32 s12, s28, 0x80000
	global_load_lds_dwordx4 v136, s[28:29]
	s_addc_u32 s13, s29, 0
	s_add_i32 m0, s43, 0x14000
	v_lshl_or_b32 v130, v5, 12, v2
	global_load_lds_dwordx4 v132, s[12:13]
	s_add_i32 m0, s43, 0x16000
	v_lshl_or_b32 v134, v4, 12, v2
	global_load_lds_dwordx4 v136, s[12:13]
	s_add_u32 s12, s37, s6
	s_addc_u32 s13, s38, s7
	s_add_i32 s44, s43, 0x2000
	s_mov_b32 m0, s43
	s_add_u32 s6, s12, 0x80000
	global_load_lds_dwordx4 v130, s[12:13]
	s_mov_b32 m0, s44
	s_addc_u32 s7, s13, 0
	s_add_i32 s45, s43, 0x4000
	global_load_lds_dwordx4 v134, s[12:13]
	s_mov_b32 m0, s45
	s_add_i32 s46, s43, 0x6000
	global_load_lds_dwordx4 v130, s[6:7]
	s_mov_b32 m0, s46
	v_mov_b32_e32 v133, 0
	global_load_lds_dwordx4 v134, s[6:7]
	v_mov_b32_e32 v137, v133
	v_mov_b32_e32 v131, v133
	v_mov_b32_e32 v135, v133
	v_lshl_add_u64 v[8:9], s[28:29], 0, v[132:133]
	v_lshl_add_u64 v[6:7], s[28:29], 0, v[136:137]
	v_lshl_add_u64 v[4:5], s[12:13], 0, v[130:131]
	s_cmp_lg_u32 s36, 1
	v_lshl_add_u64 v[2:3], s[12:13], 0, v[134:135]
	s_cbranch_scc1 .LBB0_620
	s_barrier
.LBB0_620:
	s_mov_b64 s[16:17], 0x80
	s_and_b32 s9, s11, 3
	s_add_i32 m0, s43, 0x18000
	v_lshl_add_u64 v[8:9], v[8:9], 0, s[16:17]
	s_lshl_b32 s5, s36, 13
	s_lshl_b32 s18, s9, 12
	s_waitcnt vmcnt(2)
	s_barrier
	global_load_lds_dwordx4 v[8:9], off
	v_lshl_add_u64 v[6:7], v[6:7], 0, s[16:17]
	s_add_i32 m0, s43, 0x1a000
	s_add_i32 s47, s43, 0x8000
	s_add_i32 s48, s43, 0xa000
	global_load_lds_dwordx4 v[6:7], off
	v_lshl_add_u64 v[4:5], v[4:5], 0, s[16:17]
	s_mov_b32 m0, s47
	s_add_u32 s6, s28, 0x80080
	global_load_lds_dwordx4 v[4:5], off
	v_lshl_add_u64 v[2:3], v[2:3], 0, s[16:17]
	s_mov_b32 m0, s48
	s_addc_u32 s7, s29, 0
	global_load_lds_dwordx4 v[2:3], off
	s_add_i32 m0, s43, 0x1c000
	v_lshl_add_u64 v[2:3], s[6:7], 0, v[132:133]
	global_load_lds_dwordx4 v[2:3], off
	v_lshl_add_u64 v[2:3], s[6:7], 0, v[136:137]
	s_add_i32 m0, s43, 0x1e000
	v_and_b32_e32 v1, 15, v0
	global_load_lds_dwordx4 v[2:3], off
	s_load_dwordx2 s[14:15], s[0:1], 0x0
	s_load_dwordx2 s[6:7], s[0:1], 0xa0
	v_and_b32_e32 v2, 48, v0
	v_lshlrev_b32_e32 v3, 6, v0
	s_movk_i32 s0, 0x3c0
	v_lshlrev_b32_e32 v4, 2, v0
	v_and_or_b32 v3, v3, s0, v2
	v_and_b32_e32 v4, 32, v4
	v_lshl_or_b32 v2, v1, 6, v2
	v_bitop3_b32 v6, v2, s5, v4 bitop3:0xde
	v_lshlrev_b32_e32 v2, 5, v13
	v_bitop3_b32 v151, s18, v3, v4 bitop3:0xf6
	v_and_b32_e32 v2, 0x70000, v2
	v_lshlrev_b32_e32 v4, 12, v12
	v_or3_b32 v2, v10, v2, v4
	s_mov_b64 s[0:1], 0x80080
	v_add_u32_e32 v2, v2, v11
	v_mov_b32_e32 v3, v133
	v_lshl_add_u64 v[138:139], v[2:3], 0, s[0:1]
	v_lshlrev_b32_e32 v2, 9, v0
	v_and_b32_e32 v2, 0x30000, v2
	v_or3_b32 v2, v10, v2, v4
	s_waitcnt vmcnt(6)
	v_add_u32_e32 v2, v2, v11
	v_lshl_add_u64 v[140:141], v[2:3], 0, s[0:1]
	v_add_u32_e32 v152, 0, v6
	s_sext_i32_i8 s10, s4
	v_lshl_or_b32 v204, s36, 6, v1
	s_mov_b32 s49, 0
	v_mov_b64_e32 v[142:143], 0x100
	v_mov_b64_e32 v[144:145], 0xff
	s_add_i32 s50, 0, 0x10000
	s_add_i32 s51, 0, 0x14000
	s_mov_b32 s62, 0x0da24260
	s_mov_b32 s63, 0x7fffffff
	v_max_f32_e64 v254, |v146|, s62
	v_bfi_b32 v146, s63, v254, v146
	v_max_f32_e64 v254, |v147|, s62
	v_bfi_b32 v147, s63, v254, v147
	v_max_f32_e64 v254, |v148|, s62
	v_bfi_b32 v148, s63, v254, v148
	v_max_f32_e64 v254, |v149|, s62
	v_bfi_b32 v149, s63, v254, v149
	v_max_f32_e64 v254, |v242|, s62
	v_bfi_b32 v242, s63, v254, v242
	v_max_f32_e64 v254, |v243|, s62
	v_bfi_b32 v243, s63, v254, v243
	v_max_f32_e64 v254, |v244|, s62
	v_bfi_b32 v244, s63, v254, v244
	v_max_f32_e64 v254, |v245|, s62
	v_bfi_b32 v245, s63, v254, v245
	v_max_f32_e64 v254, |v246|, s62
	v_bfi_b32 v246, s63, v254, v246
	v_max_f32_e64 v254, |v247|, s62
	v_bfi_b32 v247, s63, v254, v247
	v_max_f32_e64 v254, |v248|, s62
	v_bfi_b32 v248, s63, v254, v248
	v_max_f32_e64 v254, |v249|, s62
	v_bfi_b32 v249, s63, v254, v249
	v_max_f32_e64 v254, |v250|, s62
	v_bfi_b32 v250, s63, v254, v250
	v_max_f32_e64 v254, |v251|, s62
	v_bfi_b32 v251, s63, v254, v251
	v_max_f32_e64 v254, |v252|, s62
	v_bfi_b32 v252, s63, v254, v252
	v_max_f32_e64 v254, |v253|, s62
	v_bfi_b32 v253, s63, v254, v253
	v_rcp_f32_e32 v146, v146
	v_rcp_f32_e32 v147, v147
	v_rcp_f32_e32 v148, v148
	v_rcp_f32_e32 v149, v149
	v_rcp_f32_e32 v242, v242
	v_rcp_f32_e32 v243, v243
	v_rcp_f32_e32 v244, v244
	v_rcp_f32_e32 v245, v245
	v_rcp_f32_e32 v246, v246
	v_rcp_f32_e32 v247, v247
	v_rcp_f32_e32 v248, v248
	v_rcp_f32_e32 v249, v249
	v_rcp_f32_e32 v250, v250
	v_rcp_f32_e32 v251, v251
	v_rcp_f32_e32 v252, v252
	v_rcp_f32_e32 v253, v253
	s_nop 0
	v_mul_f32_e32 v124, v124, v244
	v_mul_f32_e32 v125, v125, v245
	v_mul_f32_e32 v128, v128, v148
	v_mul_f32_e32 v129, v129, v149
	v_mul_f32_e32 v126, v126, v146
	v_mul_f32_e32 v127, v127, v147
	v_mul_f32_e32 v122, v122, v242
	v_mul_f32_e32 v123, v123, v243
	v_mul_f32_e32 v120, v120, v248
	v_mul_f32_e32 v121, v121, v249
	v_mul_f32_e32 v118, v118, v246
	v_mul_f32_e32 v119, v119, v247
	v_mul_f32_e32 v116, v116, v252
	v_mul_f32_e32 v117, v117, v253
	v_mul_f32_e32 v114, v114, v250
	v_mul_f32_e32 v115, v115, v251
	v_mul_f32_e32 v112, v112, v148
	v_mul_f32_e32 v113, v113, v149
	v_mul_f32_e32 v110, v110, v146
	v_mul_f32_e32 v111, v111, v147
	v_mul_f32_e32 v108, v108, v244
	v_mul_f32_e32 v109, v109, v245
	v_mul_f32_e32 v106, v106, v242
	v_mul_f32_e32 v107, v107, v243
	v_mul_f32_e32 v104, v104, v248
	v_mul_f32_e32 v105, v105, v249
	v_mul_f32_e32 v102, v102, v246
	v_mul_f32_e32 v103, v103, v247
	v_mul_f32_e32 v100, v100, v252
	v_mul_f32_e32 v101, v101, v253
	v_mul_f32_e32 v98, v98, v250
	v_mul_f32_e32 v99, v99, v251
	v_mul_f32_e32 v96, v96, v148
	v_mul_f32_e32 v97, v97, v149
	v_mul_f32_e32 v94, v94, v146
	v_mul_f32_e32 v95, v95, v147
	v_mul_f32_e32 v92, v92, v244
	v_mul_f32_e32 v93, v93, v245
	v_mul_f32_e32 v90, v90, v242
	v_mul_f32_e32 v91, v91, v243
	v_mul_f32_e32 v88, v88, v248
	v_mul_f32_e32 v89, v89, v249
	v_mul_f32_e32 v86, v86, v246
	v_mul_f32_e32 v87, v87, v247
	v_mul_f32_e32 v80, v156, v252
	v_mul_f32_e32 v81, v157, v253
	v_mul_f32_e32 v78, v154, v250
	v_mul_f32_e32 v79, v155, v251
	v_mul_f32_e32 v84, v84, v148
	v_mul_f32_e32 v85, v85, v149
	v_mul_f32_e32 v82, v82, v146
	v_mul_f32_e32 v83, v83, v147
	v_mul_f32_e32 v76, v160, v244
	v_mul_f32_e32 v77, v161, v245
	v_mul_f32_e32 v74, v158, v242
	v_mul_f32_e32 v75, v159, v243
	v_mul_f32_e32 v72, v164, v248
	v_mul_f32_e32 v73, v165, v249
	v_mul_f32_e32 v70, v162, v246
	v_mul_f32_e32 v71, v163, v247
	v_mul_f32_e32 v68, v168, v252
	v_mul_f32_e32 v69, v169, v253
	v_mul_f32_e32 v66, v166, v250
	v_mul_f32_e32 v67, v167, v251
	v_mul_f32_e32 v64, v172, v148
	v_mul_f32_e32 v65, v173, v149
	v_mul_f32_e32 v62, v170, v146
	v_mul_f32_e32 v63, v171, v147
	v_mul_f32_e32 v60, v176, v244
	v_mul_f32_e32 v61, v177, v245
	v_mul_f32_e32 v58, v174, v242
	v_mul_f32_e32 v59, v175, v243
	v_mul_f32_e32 v56, v180, v248
	v_mul_f32_e32 v57, v181, v249
	v_mul_f32_e32 v54, v178, v246
	v_mul_f32_e32 v55, v179, v247
	v_mul_f32_e32 v52, v184, v252
	v_mul_f32_e32 v53, v185, v253
	v_mul_f32_e32 v50, v182, v250
	v_mul_f32_e32 v51, v183, v251
	v_mul_f32_e32 v48, v188, v148
	v_mul_f32_e32 v49, v189, v149
	v_mul_f32_e32 v46, v186, v146
	v_mul_f32_e32 v47, v187, v147
	v_mul_f32_e32 v44, v192, v244
	v_mul_f32_e32 v45, v193, v245
	v_mul_f32_e32 v42, v190, v242
	v_mul_f32_e32 v43, v191, v243
	v_mul_f32_e32 v40, v196, v248
	v_mul_f32_e32 v41, v197, v249
	v_mul_f32_e32 v38, v194, v246
	v_mul_f32_e32 v39, v195, v247
	v_mul_f32_e32 v36, v200, v252
	v_mul_f32_e32 v37, v201, v253
	v_mul_f32_e32 v34, v198, v250
	v_mul_f32_e32 v35, v199, v251
	v_mul_f32_e32 v32, v208, v148
	v_mul_f32_e32 v33, v209, v149
	v_mul_f32_e32 v30, v206, v146
	v_mul_f32_e32 v31, v207, v147
	v_mul_f32_e32 v28, v212, v244
	v_mul_f32_e32 v29, v213, v245
	v_mul_f32_e32 v26, v210, v242
	v_mul_f32_e32 v27, v211, v243
	v_mul_f32_e32 v24, v216, v248
	v_mul_f32_e32 v25, v217, v249
	v_mul_f32_e32 v22, v214, v246
	v_mul_f32_e32 v23, v215, v247
	v_mul_f32_e32 v16, v220, v252
	v_mul_f32_e32 v17, v221, v253
	v_mul_f32_e32 v14, v218, v250
	v_mul_f32_e32 v15, v219, v251
	v_mul_f32_e32 v20, v224, v148
	v_mul_f32_e32 v21, v225, v149
	v_mul_f32_e32 v18, v222, v146
	v_mul_f32_e32 v19, v223, v147
	v_mul_f32_e32 v12, v228, v244
	v_mul_f32_e32 v13, v229, v245
	v_mul_f32_e32 v10, v226, v242
	v_mul_f32_e32 v11, v227, v243
	v_mul_f32_e32 v8, v232, v248
	v_mul_f32_e32 v9, v233, v249
	v_mul_f32_e32 v6, v230, v246
	v_mul_f32_e32 v7, v231, v247
	v_mul_f32_e32 v4, v236, v252
	v_mul_f32_e32 v5, v237, v253
	v_mul_f32_e32 v2, v234, v250
	v_mul_f32_e32 v3, v235, v251
	s_barrier
	s_branch .LBB0_623

.LBB0_635:
	s_lshl_b32 s0, s9, 5
	s_lshl_b32 s1, s10, 8
	s_or_b32 s0, s1, s0
	v_and_or_b32 v130, v150, 24, s0
	s_ashr_i32 s0, s8, 31
	s_lshr_b32 s0, s0, 28
	s_add_i32 s0, s8, s0
	s_ashr_i32 s0, s0, 4
	s_mul_hi_i32 s1, s0, 0x6000
	s_mulk_i32 s0, 0x6000
	s_add_u32 s0, s24, s0
	v_ashrrev_i32_e32 v131, 31, v130
	s_addc_u32 s1, s25, s1
	v_lshlrev_b64 v[194:195], 2, v[130:131]
	s_lshl_b32 s4, s8, 8
	v_lshl_add_u64 v[130:131], s[0:1], 0, v[194:195]
	s_mov_b32 s2, 0x2904000
	v_add_u32_e32 v196, s4, v204
	v_add_co_u32_e32 v132, vcc, s2, v130
	v_ashrrev_i32_e32 v197, 31, v196
	s_nop 0
	v_addc_co_u32_e32 v133, vcc, 0, v131, vcc
	v_lshl_add_u64 v[202:203], s[14:15], 0, v[194:195]
	v_lshlrev_b64 v[198:199], 13, v[196:197]
	s_barrier
	flat_load_dwordx4 v[134:137], v[132:133]
	v_lshl_add_u64 v[132:133], v[202:203], 0, v[198:199]
	s_mov_b64 s[0:1], 0x2904000
	v_lshl_add_u64 v[130:131], v[130:131], 0, s[0:1]
	flat_load_dwordx4 v[142:145], v[130:131] offset:16
	flat_load_dwordx4 v[138:141], v[130:131] offset:512
	s_nop 0
	flat_load_dwordx4 v[130:133], v[130:131] offset:528
	v_or_b32_e32 v146, 16, v196
	v_ashrrev_i32_e32 v147, 31, v146
	v_lshlrev_b64 v[146:147], 13, v[146:147]
	v_lshl_add_u64 v[146:147], v[202:203], 0, v[146:147]
	v_or_b32_e32 v146, 32, v196
	v_ashrrev_i32_e32 v147, 31, v146
	v_lshlrev_b64 v[146:147], 13, v[146:147]
	v_lshl_add_u64 v[146:147], v[202:203], 0, v[146:147]
	v_or_b32_e32 v146, 48, v196
	v_ashrrev_i32_e32 v147, 31, v146
	v_lshlrev_b64 v[146:147], 13, v[146:147]
	v_lshl_add_u64 v[150:151], v[202:203], 0, v[146:147]
	s_nop 0
	v_mbcnt_lo_u32_b32 v200, -1, 0
	v_mbcnt_hi_u32_b32 v200, -1, v200
	v_and_b32_e32 v205, 64, v200
	v_xor_b32_e32 v201, 16, v200
	v_add_u32_e32 v222, 64, v205
	v_cmp_lt_i32_e32 vcc, v201, v222
	v_and_b32_e32 v197, 63, v0
	s_lshl_b32 s0, s9, 2
	v_cndmask_b32_e32 v201, v200, v201, vcc
	v_lshlrev_b32_e32 v205, 2, v201
	v_lshlrev_b32_e32 v1, 4, v1
	s_add_i32 s2, s0, 0
	s_waitcnt vmcnt(0) lgkmcnt(0)
	s_mov_b32 s62, 0x0da24260
	s_mov_b32 s63, 0x7fffffff
	v_max_f32_e64 v254, |v130|, s62
	v_bfi_b32 v130, s63, v254, v130
	v_max_f32_e64 v254, |v131|, s62
	v_bfi_b32 v131, s63, v254, v131
	v_max_f32_e64 v254, |v132|, s62
	v_bfi_b32 v132, s63, v254, v132
	v_max_f32_e64 v254, |v133|, s62
	v_bfi_b32 v133, s63, v254, v133
	v_max_f32_e64 v254, |v134|, s62
	v_bfi_b32 v134, s63, v254, v134
	v_max_f32_e64 v254, |v135|, s62
	v_bfi_b32 v135, s63, v254, v135
	v_max_f32_e64 v254, |v136|, s62
	v_bfi_b32 v136, s63, v254, v136
	v_max_f32_e64 v254, |v137|, s62
	v_bfi_b32 v137, s63, v254, v137
	v_max_f32_e64 v254, |v138|, s62
	v_bfi_b32 v138, s63, v254, v138
	v_max_f32_e64 v254, |v139|, s62
	v_bfi_b32 v139, s63, v254, v139
	v_max_f32_e64 v254, |v140|, s62
	v_bfi_b32 v140, s63, v254, v140
	v_max_f32_e64 v254, |v141|, s62
	v_bfi_b32 v141, s63, v254, v141
	v_max_f32_e64 v254, |v142|, s62
	v_bfi_b32 v142, s63, v254, v142
	v_max_f32_e64 v254, |v143|, s62
	v_bfi_b32 v143, s63, v254, v143
	v_max_f32_e64 v254, |v144|, s62
	v_bfi_b32 v144, s63, v254, v144
	v_max_f32_e64 v254, |v145|, s62
	v_bfi_b32 v145, s63, v254, v145
	v_pk_mul_f32 v[124:125], v[124:125], v[144:145]
	v_pk_mul_f32 v[128:129], v[128:129], v[136:137]
	v_pk_mul_f32 v[126:127], v[126:127], v[134:135]
	v_pk_mul_f32 v[122:123], v[122:123], v[142:143]
	v_mul_f32_e32 v201, v127, v127
	v_mul_f32_e32 v206, v129, v129
	v_mul_f32_e32 v207, v123, v123
	v_mul_f32_e32 v208, v125, v125
	v_pk_mul_f32 v[120:121], v[120:121], v[140:141]
	v_pk_mul_f32 v[118:119], v[118:119], v[138:139]
	v_fmac_f32_e32 v201, v126, v126
	v_fmac_f32_e32 v206, v128, v128
	v_fmac_f32_e32 v207, v122, v122
	v_fmac_f32_e32 v208, v124, v124
	v_pk_mul_f32 v[116:117], v[116:117], v[132:133]
	v_pk_mul_f32 v[114:115], v[114:115], v[130:131]
	v_mul_f32_e32 v209, v119, v119
	v_mul_f32_e32 v210, v121, v121
	v_add_f32_e32 v201, v201, v206
	v_add_f32_e32 v206, v207, v208
	v_mul_f32_e32 v211, v115, v115
	v_fmac_f32_e32 v209, v118, v118
	v_fmac_f32_e32 v210, v120, v120
	v_add_f32_e32 v201, v201, v206
	v_mul_f32_e32 v206, v117, v117
	v_add_f32_e32 v207, v209, v210
	v_fmac_f32_e32 v211, v114, v114
	v_fmac_f32_e32 v206, v116, v116
	v_add_f32_e32 v201, v201, v207
	v_add_f32_e32 v206, v211, v206
	v_add_f32_e32 v201, v201, v206
	ds_bpermute_b32 v207, v205, v201
	v_xor_b32_e32 v206, 32, v200
	v_cmp_lt_i32_e32 vcc, v206, v222
	s_nop 1
	v_cndmask_b32_e32 v200, v200, v206, vcc
	v_lshlrev_b32_e32 v206, 2, v200
	s_waitcnt lgkmcnt(0)
	v_add_f32_e32 v200, v201, v207
	ds_bpermute_b32 v201, v206, v200
	v_cmp_gt_u32_e32 vcc, 16, v197
	s_and_saveexec_b64 s[0:1], vcc
	s_cbranch_execz .LBB0_637
	s_lshl_b32 s3, s36, 10
	s_add_i32 s3, s2, s3
	v_add_u32_e32 v207, s3, v1
	s_waitcnt lgkmcnt(0)
	v_add_f32_e32 v200, v200, v201
	ds_write_b32 v207, v200
.LBB0_637:
	s_or_b64 exec, exec, s[0:1]
	v_pk_mul_f32 v[192:193], v[112:113], v[136:137]
	v_pk_mul_f32 v[190:191], v[110:111], v[134:135]
	v_pk_mul_f32 v[188:189], v[108:109], v[144:145]
	v_pk_mul_f32 v[186:187], v[106:107], v[142:143]
	v_mul_f32_e32 v110, v191, v191
	v_mul_f32_e32 v111, v193, v193
	v_mul_f32_e32 v106, v187, v187
	v_mul_f32_e32 v107, v189, v189
	v_pk_mul_f32 v[184:185], v[104:105], v[140:141]
	v_pk_mul_f32 v[182:183], v[102:103], v[138:139]
	v_fmac_f32_e32 v110, v190, v190
	v_fmac_f32_e32 v111, v192, v192
	v_fmac_f32_e32 v106, v186, v186
	v_fmac_f32_e32 v107, v188, v188
	v_mul_f32_e32 v102, v183, v183
	v_mul_f32_e32 v103, v185, v185
	v_pk_mul_f32 v[180:181], v[100:101], v[132:133]
	v_pk_mul_f32 v[178:179], v[98:99], v[130:131]
	v_add_f32_e32 v110, v110, v111
	v_add_f32_e32 v106, v106, v107
	v_fmac_f32_e32 v102, v182, v182
	v_fmac_f32_e32 v103, v184, v184
	v_mul_f32_e32 v98, v179, v179
	v_mul_f32_e32 v99, v181, v181
	v_add_f32_e32 v106, v110, v106
	v_add_f32_e32 v102, v102, v103
	v_fmac_f32_e32 v98, v178, v178
	v_fmac_f32_e32 v99, v180, v180
	v_add_f32_e32 v102, v106, v102
	v_add_f32_e32 v98, v98, v99
	v_add_f32_e32 v98, v102, v98
	ds_bpermute_b32 v99, v205, v98
	s_waitcnt lgkmcnt(0)
	v_add_f32_e32 v98, v98, v99
	ds_bpermute_b32 v99, v206, v98
	s_and_saveexec_b64 s[0:1], vcc
	s_cbranch_execz .LBB0_639
	s_lshl_b32 s3, s36, 10
	s_add_i32 s3, s2, s3
	v_add_u32_e32 v100, s3, v1
	s_waitcnt lgkmcnt(0)
	v_add_f32_e32 v98, v98, v99
	ds_write_b32 v100, v98 offset:256
.LBB0_639:
	s_or_b64 exec, exec, s[0:1]
	v_pk_mul_f32 v[176:177], v[96:97], v[136:137]
	v_pk_mul_f32 v[174:175], v[94:95], v[134:135]
	v_pk_mul_f32 v[172:173], v[92:93], v[144:145]
	v_pk_mul_f32 v[170:171], v[90:91], v[142:143]
	v_mul_f32_e32 v94, v175, v175
	v_mul_f32_e32 v95, v177, v177
	v_mul_f32_e32 v90, v171, v171
	v_mul_f32_e32 v91, v173, v173
	v_pk_mul_f32 v[168:169], v[88:89], v[140:141]
	v_pk_mul_f32 v[200:201], v[86:87], v[138:139]
	v_fmac_f32_e32 v94, v174, v174
	v_fmac_f32_e32 v95, v176, v176
	v_fmac_f32_e32 v90, v170, v170
	v_fmac_f32_e32 v91, v172, v172
	v_mul_f32_e32 v86, v201, v201
	v_mul_f32_e32 v87, v169, v169
	v_pk_mul_f32 v[164:165], v[80:81], v[132:133]
	v_pk_mul_f32 v[162:163], v[78:79], v[130:131]
	v_add_f32_e32 v94, v94, v95
	v_add_f32_e32 v90, v90, v91
	v_fmac_f32_e32 v86, v200, v200
	v_fmac_f32_e32 v87, v168, v168
	v_mul_f32_e32 v78, v163, v163
	v_mul_f32_e32 v79, v165, v165
	v_add_f32_e32 v90, v94, v90
	v_add_f32_e32 v86, v86, v87
	v_fmac_f32_e32 v78, v162, v162
	v_fmac_f32_e32 v79, v164, v164
	v_add_f32_e32 v86, v90, v86
	v_add_f32_e32 v78, v78, v79
	v_add_f32_e32 v78, v86, v78
	ds_bpermute_b32 v79, v205, v78
	s_waitcnt lgkmcnt(0)
	v_add_f32_e32 v78, v78, v79
	ds_bpermute_b32 v79, v206, v78
	s_and_saveexec_b64 s[0:1], vcc
	s_cbranch_execz .LBB0_641
	s_lshl_b32 s3, s36, 10
	s_add_i32 s3, s2, s3
	v_add_u32_e32 v80, s3, v1
	s_waitcnt lgkmcnt(0)
	v_add_f32_e32 v78, v78, v79
	ds_write_b32 v80, v78 offset:512
.LBB0_641:
	s_or_b64 exec, exec, s[0:1]
	v_pk_mul_f32 v[160:161], v[84:85], v[136:137]
	v_pk_mul_f32 v[158:159], v[82:83], v[134:135]
	v_pk_mul_f32 v[156:157], v[76:77], v[144:145]
	v_pk_mul_f32 v[154:155], v[74:75], v[142:143]
	v_mul_f32_e32 v78, v159, v159
	s_waitcnt lgkmcnt(0)
	v_mul_f32_e32 v79, v161, v161
	v_mul_f32_e32 v74, v155, v155
	v_mul_f32_e32 v75, v157, v157
	v_pk_mul_f32 v[152:153], v[72:73], v[140:141]
	v_pk_mul_f32 v[150:151], v[70:71], v[138:139]
	v_fmac_f32_e32 v78, v158, v158
	v_fmac_f32_e32 v79, v160, v160
	v_fmac_f32_e32 v74, v154, v154
	v_fmac_f32_e32 v75, v156, v156
	v_mul_f32_e32 v70, v151, v151
	v_mul_f32_e32 v71, v153, v153
	v_pk_mul_f32 v[148:149], v[68:69], v[132:133]
	v_pk_mul_f32 v[146:147], v[66:67], v[130:131]
	v_add_f32_e32 v78, v78, v79
	v_add_f32_e32 v74, v74, v75
	v_fmac_f32_e32 v70, v150, v150
	v_fmac_f32_e32 v71, v152, v152
	v_mul_f32_e32 v66, v147, v147
	v_mul_f32_e32 v67, v149, v149
	v_add_f32_e32 v74, v78, v74
	v_add_f32_e32 v70, v70, v71
	v_fmac_f32_e32 v66, v146, v146
	v_fmac_f32_e32 v67, v148, v148
	v_add_f32_e32 v70, v74, v70
	v_add_f32_e32 v66, v66, v67
	v_add_f32_e32 v66, v70, v66
	ds_bpermute_b32 v67, v205, v66
	s_waitcnt lgkmcnt(0)
	v_add_f32_e32 v66, v66, v67
	ds_bpermute_b32 v67, v206, v66
	s_and_saveexec_b64 s[0:1], vcc
	s_cbranch_execz .LBB0_643
	s_lshl_b32 s3, s36, 10
	s_add_i32 s3, s2, s3
	v_add_u32_e32 v68, s3, v1
	s_waitcnt lgkmcnt(0)
	v_add_f32_e32 v66, v66, v67
	ds_write_b32 v68, v66 offset:768
.LBB0_643:
	s_or_b64 exec, exec, s[0:1]
	v_add_u32_e32 v66, 0x80, v196
	s_waitcnt lgkmcnt(0)
	v_ashrrev_i32_e32 v67, 31, v66
	v_lshlrev_b64 v[166:167], 13, v[66:67]
	v_lshl_add_u64 v[66:67], v[202:203], 0, v[166:167]
	v_add_u32_e32 v66, 0x90, v196
	v_add_u32_e32 v68, 0xa0, v196
	v_add_u32_e32 v70, 0xb0, v196
	v_ashrrev_i32_e32 v67, 31, v66
	v_ashrrev_i32_e32 v69, 31, v68
	v_ashrrev_i32_e32 v71, 31, v70
	v_lshlrev_b64 v[66:67], 13, v[66:67]
	v_lshlrev_b64 v[68:69], 13, v[68:69]
	v_lshlrev_b64 v[70:71], 13, v[70:71]
	v_lshl_add_u64 v[66:67], v[202:203], 0, v[66:67]
	v_lshl_add_u64 v[68:69], v[202:203], 0, v[68:69]
	v_lshl_add_u64 v[70:71], v[202:203], 0, v[70:71]
	s_nop 0
	s_nop 0
	s_waitcnt vmcnt(15)
	v_pk_mul_f32 v[64:65], v[64:65], v[136:137]
	v_pk_mul_f32 v[62:63], v[62:63], v[134:135]
	s_waitcnt vmcnt(14)
	v_pk_mul_f32 v[60:61], v[60:61], v[144:145]
	v_pk_mul_f32 v[58:59], v[58:59], v[142:143]
	s_waitcnt vmcnt(13)
	v_pk_mul_f32 v[56:57], v[56:57], v[140:141]
	v_pk_mul_f32 v[54:55], v[54:55], v[138:139]
	v_mul_f32_e32 v202, v63, v63
	v_mul_f32_e32 v203, v65, v65
	v_mul_f32_e32 v207, v59, v59
	v_mul_f32_e32 v208, v61, v61
	s_waitcnt vmcnt(12)
	v_pk_mul_f32 v[52:53], v[52:53], v[132:133]
	v_pk_mul_f32 v[50:51], v[50:51], v[130:131]
	v_mul_f32_e32 v209, v55, v55
	v_mul_f32_e32 v210, v57, v57
	v_fmac_f32_e32 v202, v62, v62
	v_fmac_f32_e32 v203, v64, v64
	v_fmac_f32_e32 v207, v58, v58
	v_fmac_f32_e32 v208, v60, v60
	v_mul_f32_e32 v211, v51, v51
	v_mul_f32_e32 v212, v53, v53
	v_fmac_f32_e32 v209, v54, v54
	v_fmac_f32_e32 v210, v56, v56
	v_add_f32_e32 v202, v202, v203
	v_add_f32_e32 v203, v207, v208
	v_fmac_f32_e32 v211, v50, v50
	v_fmac_f32_e32 v212, v52, v52
	v_add_f32_e32 v207, v209, v210
	v_add_f32_e32 v202, v202, v203
	v_add_f32_e32 v202, v202, v207
	v_add_f32_e32 v203, v211, v212
	v_add_f32_e32 v202, v202, v203
	ds_bpermute_b32 v203, v205, v202
	s_waitcnt lgkmcnt(0)
	v_add_f32_e32 v202, v202, v203
	ds_bpermute_b32 v203, v206, v202
	s_and_saveexec_b64 s[0:1], vcc
	s_cbranch_execz .LBB0_645
	s_lshl_b32 s3, s36, 10
	s_add_i32 s3, s2, s3
	v_add_u32_e32 v207, s3, v1
	s_waitcnt lgkmcnt(0)
	v_add_f32_e32 v202, v202, v203
	ds_write_b32 v207, v202 offset:2048
.LBB0_645:
	s_or_b64 exec, exec, s[0:1]
	s_waitcnt vmcnt(10)
	v_pk_mul_f32 v[48:49], v[48:49], v[136:137]
	v_pk_mul_f32 v[46:47], v[46:47], v[134:135]
	v_pk_mul_f32 v[44:45], v[44:45], v[144:145]
	v_pk_mul_f32 v[42:43], v[42:43], v[142:143]
	v_mul_f32_e32 v110, v47, v47
	v_mul_f32_e32 v111, v49, v49
	v_mul_f32_e32 v106, v43, v43
	v_mul_f32_e32 v107, v45, v45
	s_waitcnt vmcnt(8)
	v_pk_mul_f32 v[40:41], v[40:41], v[140:141]
	v_pk_mul_f32 v[38:39], v[38:39], v[138:139]
	v_fmac_f32_e32 v110, v46, v46
	v_fmac_f32_e32 v111, v48, v48
	v_fmac_f32_e32 v106, v42, v42
	v_fmac_f32_e32 v107, v44, v44
	v_mul_f32_e32 v102, v39, v39
	v_mul_f32_e32 v103, v41, v41
	v_pk_mul_f32 v[36:37], v[36:37], v[132:133]
	v_pk_mul_f32 v[34:35], v[34:35], v[130:131]
	v_add_f32_e32 v110, v110, v111
	v_add_f32_e32 v106, v106, v107
	v_fmac_f32_e32 v102, v38, v38
	v_fmac_f32_e32 v103, v40, v40
	v_mul_f32_e32 v98, v35, v35
	v_mul_f32_e32 v99, v37, v37
	v_add_f32_e32 v106, v110, v106
	v_add_f32_e32 v102, v102, v103
	v_fmac_f32_e32 v98, v34, v34
	v_fmac_f32_e32 v99, v36, v36
	v_add_f32_e32 v102, v106, v102
	v_add_f32_e32 v98, v98, v99
	v_add_f32_e32 v98, v102, v98
	ds_bpermute_b32 v99, v205, v98
	s_waitcnt lgkmcnt(0)
	v_add_f32_e32 v98, v98, v99
	ds_bpermute_b32 v99, v206, v98
	s_and_saveexec_b64 s[0:1], vcc
	s_cbranch_execz .LBB0_647
	s_lshl_b32 s3, s36, 10
	s_add_i32 s3, s2, s3
	v_add_u32_e32 v100, s3, v1
	s_waitcnt lgkmcnt(0)
	v_add_f32_e32 v98, v98, v99
	ds_write_b32 v100, v98 offset:2304
.LBB0_647:
	s_or_b64 exec, exec, s[0:1]
	s_waitcnt vmcnt(6)
	v_pk_mul_f32 v[32:33], v[32:33], v[136:137]
	v_pk_mul_f32 v[30:31], v[30:31], v[134:135]
	v_pk_mul_f32 v[28:29], v[28:29], v[144:145]
	v_pk_mul_f32 v[26:27], v[26:27], v[142:143]
	v_mul_f32_e32 v94, v31, v31
	v_mul_f32_e32 v95, v33, v33
	v_mul_f32_e32 v90, v27, v27
	v_mul_f32_e32 v91, v29, v29
	s_waitcnt vmcnt(4)
	v_pk_mul_f32 v[24:25], v[24:25], v[140:141]
	v_pk_mul_f32 v[22:23], v[22:23], v[138:139]
	v_fmac_f32_e32 v94, v30, v30
	v_fmac_f32_e32 v95, v32, v32
	v_fmac_f32_e32 v90, v26, v26
	v_fmac_f32_e32 v91, v28, v28
	v_mul_f32_e32 v86, v23, v23
	v_mul_f32_e32 v87, v25, v25
	v_pk_mul_f32 v[16:17], v[16:17], v[132:133]
	v_pk_mul_f32 v[82:83], v[14:15], v[130:131]
	v_add_f32_e32 v94, v94, v95
	v_add_f32_e32 v90, v90, v91
	v_fmac_f32_e32 v86, v22, v22
	v_fmac_f32_e32 v87, v24, v24
	v_mul_f32_e32 v14, v83, v83
	v_mul_f32_e32 v15, v17, v17
	v_add_f32_e32 v90, v94, v90
	v_add_f32_e32 v86, v86, v87
	v_fmac_f32_e32 v14, v82, v82
	v_fmac_f32_e32 v15, v16, v16
	v_add_f32_e32 v86, v90, v86
	v_add_f32_e32 v14, v14, v15
	v_add_f32_e32 v14, v86, v14
	ds_bpermute_b32 v15, v205, v14
	s_waitcnt lgkmcnt(0)
	v_add_f32_e32 v14, v14, v15
	ds_bpermute_b32 v15, v206, v14
	s_and_saveexec_b64 s[0:1], vcc
	s_cbranch_execz .LBB0_649
	s_lshl_b32 s3, s36, 10
	s_add_i32 s3, s2, s3
	v_add_u32_e32 v84, s3, v1
	s_waitcnt lgkmcnt(0)
	v_add_f32_e32 v14, v14, v15
	ds_write_b32 v84, v14 offset:2560
.LBB0_649:
	s_or_b64 exec, exec, s[0:1]
	s_waitcnt vmcnt(2)
	v_pk_mul_f32 v[20:21], v[20:21], v[136:137]
	v_pk_mul_f32 v[78:79], v[18:19], v[134:135]
	v_pk_mul_f32 v[18:19], v[12:13], v[144:145]
	v_pk_mul_f32 v[74:75], v[10:11], v[142:143]
	v_mul_f32_e32 v14, v79, v79
	s_waitcnt lgkmcnt(0)
	v_mul_f32_e32 v15, v21, v21
	v_mul_f32_e32 v10, v75, v75
	v_mul_f32_e32 v11, v19, v19
	s_waitcnt vmcnt(0)
	v_pk_mul_f32 v[72:73], v[8:9], v[140:141]
	v_pk_mul_f32 v[70:71], v[6:7], v[138:139]
	v_fmac_f32_e32 v14, v78, v78
	v_fmac_f32_e32 v15, v20, v20
	v_fmac_f32_e32 v10, v74, v74
	v_fmac_f32_e32 v11, v18, v18
	v_mul_f32_e32 v6, v71, v71
	v_mul_f32_e32 v7, v73, v73
	v_pk_mul_f32 v[68:69], v[4:5], v[132:133]
	v_pk_mul_f32 v[66:67], v[2:3], v[130:131]
	v_add_f32_e32 v14, v14, v15
	v_add_f32_e32 v10, v10, v11
	v_fmac_f32_e32 v6, v70, v70
	v_fmac_f32_e32 v7, v72, v72
	v_mul_f32_e32 v2, v67, v67
	v_mul_f32_e32 v3, v69, v69
	v_add_f32_e32 v10, v14, v10
	v_add_f32_e32 v6, v6, v7
	v_fmac_f32_e32 v2, v66, v66
	v_fmac_f32_e32 v3, v68, v68
	v_add_f32_e32 v6, v10, v6
	v_add_f32_e32 v2, v2, v3
	v_add_f32_e32 v2, v6, v2
	ds_bpermute_b32 v3, v205, v2
	s_waitcnt lgkmcnt(0)
	v_add_f32_e32 v2, v2, v3
	ds_bpermute_b32 v3, v206, v2
	s_and_saveexec_b64 s[0:1], vcc
	s_cbranch_execz .LBB0_651
	s_lshl_b32 s3, s36, 10
	s_add_i32 s2, s2, s3
	v_add_u32_e32 v1, s2, v1
	s_waitcnt lgkmcnt(0)
	v_add_f32_e32 v2, v2, v3
	ds_write_b32 v1, v2 offset:2816

	.amdhsa_kernel _Z6mk_fwd4Args
		.amdhsa_group_segment_fixed_size 0
		.amdhsa_private_segment_fixed_size 0
		.amdhsa_kernarg_size 440
		.amdhsa_user_sgpr_count 2
		.amdhsa_user_sgpr_dispatch_ptr 0
		.amdhsa_user_sgpr_queue_ptr 0
		.amdhsa_user_sgpr_kernarg_segment_ptr 1
		.amdhsa_user_sgpr_dispatch_id 0
		.amdhsa_user_sgpr_kernarg_preload_length 0
		.amdhsa_user_sgpr_kernarg_preload_offset 0
		.amdhsa_user_sgpr_private_segment_size 0
		.amdhsa_uses_dynamic_stack 0
		.amdhsa_enable_private_segment 0
		.amdhsa_system_sgpr_workgroup_id_x 1
		.amdhsa_system_sgpr_workgroup_id_y 0
		.amdhsa_system_sgpr_workgroup_id_z 0
		.amdhsa_system_sgpr_workgroup_info 0
		.amdhsa_system_vgpr_workitem_id 0
		.amdhsa_next_free_vgpr 256
		.amdhsa_next_free_sgpr 102
		.amdhsa_accum_offset 256
		.amdhsa_reserve_vcc 1
		.amdhsa_float_round_mode_32 0
		.amdhsa_float_round_mode_16_64 0
		.amdhsa_float_denorm_mode_32 3
		.amdhsa_float_denorm_mode_16_64 3
		.amdhsa_dx10_clamp 1
		.amdhsa_ieee_mode 1
		.amdhsa_fp16_overflow 0
		.amdhsa_tg_split 0
		.amdhsa_exception_fp_ieee_invalid_op 0
		.amdhsa_exception_fp_denorm_src 0
		.amdhsa_exception_fp_ieee_div_zero 0
		.amdhsa_exception_fp_ieee_overflow 0
		.amdhsa_exception_fp_ieee_underflow 0
		.amdhsa_exception_fp_ieee_inexact 0
		.amdhsa_exception_int_div_zero 0
	.end_amdhsa_kernel

amdhsa.kernels:
  - .agpr_count:     0
    .args:
      - .offset:         0
        .size:           184
        .value_kind:     by_value
      - .offset:         184
        .size:           4
        .value_kind:     hidden_block_count_x
      - .offset:         188
        .size:           4
        .value_kind:     hidden_block_count_y
      - .offset:         192
        .size:           4
        .value_kind:     hidden_block_count_z
      - .offset:         196
        .size:           2
        .value_kind:     hidden_group_size_x
      - .offset:         198
        .size:           2
        .value_kind:     hidden_group_size_y
      - .offset:         200
        .size:           2
        .value_kind:     hidden_group_size_z
      - .offset:         202
        .size:           2
        .value_kind:     hidden_remainder_x
      - .offset:         204
        .size:           2
        .value_kind:     hidden_remainder_y
      - .offset:         206
        .size:           2
        .value_kind:     hidden_remainder_z
      - .offset:         224
        .size:           8
        .value_kind:     hidden_global_offset_x
      - .offset:         232
        .size:           8
        .value_kind:     hidden_global_offset_y
      - .offset:         240
        .size:           8
        .value_kind:     hidden_global_offset_z
      - .offset:         248
        .size:           2
        .value_kind:     hidden_grid_dims
      - .offset:         304
        .size:           4
        .value_kind:     hidden_dynamic_lds_size
    .group_segment_fixed_size: 0
    .kernarg_segment_align: 8
    .kernarg_segment_size: 440
    .language:       OpenCL C
    .language_version:
      - 2
      - 0
    .max_flat_workgroup_size: 512
    .name:           _Z6mk_fwd4Args
    .private_segment_fixed_size: 0
    .sgpr_count:     108
    .sgpr_spill_count: 3
    .symbol:         _Z6mk_fwd4Args.kd
    .uniform_work_group_size: 1
    .uses_dynamic_stack: false
    .vgpr_count:     256
    .vgpr_spill_count: 0
    .wavefront_size: 64
